# phase-0 weight conversion also uses the 4-deep pipelined hand routine
# speedup vs baseline: 1.0007x; 1.0007x over previous
.LBB0_48:
	s_or_b64 exec, exec, s[4:5]
	s_cmp_gt_i32 s97, -1
	s_cselect_b64 s[76:77], -1, 0
	s_cmp_lt_i32 s97, s0
	s_cselect_b64 s[2:3], -1, 0
	s_and_b64 s[2:3], s[76:77], s[2:3]
	v_mov_b32_e32 v0, v204
	s_andn2_b64 vcc, exec, s[2:3]
	s_cbranch_vccnz .LBB0_64
	s_load_dwordx2 s[18:19], s[86:87], 0xb8
	s_waitcnt lgkmcnt(0)
	v_lshrrev_b32_e32 v0, 3, v204
	v_and_b32_e32 v1, 7, v204
	v_lshlrev_b32_e32 v1, 3, v1
	v_mul_u32_u24_e32 v2, 65, v0
	v_add_lshl_u32 v2, v2, v1, 2
	v_mul_u32_u24_e32 v4, 65, v1
	v_add_lshl_u32 v4, v4, v0, 2
	s_add_u32 s39, s97, 0
	s_mov_b32 s33, s39
	s_add_u32 s35, s33, 0
	s_cmp_lt_u32 s35, 896
	s_cselect_b32 s35, s35, s39
	s_mov_b64 s[64:65], s[16:17]
	s_mov_b32 s8, 3584
	s_mov_b32 s9, 0x4924925
	s_mov_b32 s12, 56
	s_movk_i32 s13, 0
	s_add_u32 s66, s18, 0x0
	s_addc_u32 s67, s19, 0
	s_movk_i32 s14, 1024
	s_mov_b32 s15, 1
	s_add_u32 s70, s10, 0
	s_addc_u32 s71, s11, 0
.Lcv_z_p0_c:
	s_sub_u32 s0, s35, s13
	s_mul_hi_u32 s1, s0, s9
	s_mul_i32 s2, s1, s12
	s_sub_u32 s2, s0, s2
	s_lshl_b32 s1, s1, 6
	s_lshl_b32 s2, s2, 6
	s_mul_i32 s3, s1, s8
	s_lshl_b32 s3, s3, 2
	s_add_u32 s64, s64, s3
	s_addc_u32 s65, s65, 0
	v_add_u32_e32 v5, s2, v1
	s_sub_u32 s4, s8, 8
	v_min_u32_e32 v5, s4, v5
	v_mad_u32_u24 v5, v0, s8, v5
	v_lshlrev_b32_e32 v5, 2, v5
	global_load_dwordx4 v[40:43], v5, s[64:65]
	global_load_dwordx4 v[44:47], v5, s[64:65] offset:16
	s_lshl_b32 s3, s1, 2
	s_add_u32 s70, s70, s3
	s_addc_u32 s71, s71, 0
	v_lshlrev_b32_e32 v6, 2, v0
	global_load_dword v48, v6, s[70:71]
	s_mul_i32 s3, s2, s14
	s_add_u32 s3, s3, s1
	s_lshl_b32 s3, s3, 1
	s_add_u32 s40, s66, s3
	s_addc_u32 s41, s67, 0
	s_mov_b32 s42, s14
	s_sub_u32 s43, s8, s2
	s_mov_b32 s44, s15
	s_add_u32 s35, s33, 256
	s_cmp_lt_u32 s35, 896
	s_cselect_b32 s35, s35, s39
	s_mov_b64 s[64:65], s[16:17]
	s_mov_b32 s8, 3584
	s_mov_b32 s9, 0x4924925
	s_mov_b32 s12, 56
	s_movk_i32 s13, 0
	s_add_u32 s66, s18, 0x0
	s_addc_u32 s67, s19, 0
	s_movk_i32 s14, 1024
	s_mov_b32 s15, 1
	s_add_u32 s70, s10, 0
	s_addc_u32 s71, s11, 0
.Lcv_z_p1_c:
	s_sub_u32 s0, s35, s13
	s_mul_hi_u32 s1, s0, s9
	s_mul_i32 s2, s1, s12
	s_sub_u32 s2, s0, s2
	s_lshl_b32 s1, s1, 6
	s_lshl_b32 s2, s2, 6
	s_mul_i32 s3, s1, s8
	s_lshl_b32 s3, s3, 2
	s_add_u32 s64, s64, s3
	s_addc_u32 s65, s65, 0
	v_add_u32_e32 v5, s2, v1
	s_sub_u32 s4, s8, 8
	v_min_u32_e32 v5, s4, v5
	v_mad_u32_u24 v5, v0, s8, v5
	v_lshlrev_b32_e32 v5, 2, v5
	global_load_dwordx4 v[50:53], v5, s[64:65]
	global_load_dwordx4 v[54:57], v5, s[64:65] offset:16
	s_lshl_b32 s3, s1, 2
	s_add_u32 s70, s70, s3
	s_addc_u32 s71, s71, 0
	v_lshlrev_b32_e32 v6, 2, v0
	global_load_dword v58, v6, s[70:71]
	s_mul_i32 s3, s2, s14
	s_add_u32 s3, s3, s1
	s_lshl_b32 s3, s3, 1
	s_add_u32 s46, s66, s3
	s_addc_u32 s47, s67, 0
	s_mov_b32 s48, s14
	s_sub_u32 s49, s8, s2
	s_mov_b32 s50, s15
	s_add_u32 s35, s33, 512
	s_cmp_lt_u32 s35, 896
	s_cselect_b32 s35, s35, s39
	s_mov_b64 s[64:65], s[16:17]
	s_mov_b32 s8, 3584
	s_mov_b32 s9, 0x4924925
	s_mov_b32 s12, 56
	s_movk_i32 s13, 0
	s_add_u32 s66, s18, 0x0
	s_addc_u32 s67, s19, 0
	s_movk_i32 s14, 1024
	s_mov_b32 s15, 1
	s_add_u32 s70, s10, 0
	s_addc_u32 s71, s11, 0
.Lcv_z_p2_c:
	s_sub_u32 s0, s35, s13
	s_mul_hi_u32 s1, s0, s9
	s_mul_i32 s2, s1, s12
	s_sub_u32 s2, s0, s2
	s_lshl_b32 s1, s1, 6
	s_lshl_b32 s2, s2, 6
	s_mul_i32 s3, s1, s8
	s_lshl_b32 s3, s3, 2
	s_add_u32 s64, s64, s3
	s_addc_u32 s65, s65, 0
	v_add_u32_e32 v5, s2, v1
	s_sub_u32 s4, s8, 8
	v_min_u32_e32 v5, s4, v5
	v_mad_u32_u24 v5, v0, s8, v5
	v_lshlrev_b32_e32 v5, 2, v5
	global_load_dwordx4 v[60:63], v5, s[64:65]
	global_load_dwordx4 v[64:67], v5, s[64:65] offset:16
	s_lshl_b32 s3, s1, 2
	s_add_u32 s70, s70, s3
	s_addc_u32 s71, s71, 0
	v_lshlrev_b32_e32 v6, 2, v0
	global_load_dword v68, v6, s[70:71]
	s_mul_i32 s3, s2, s14
	s_add_u32 s3, s3, s1
	s_lshl_b32 s3, s3, 1
	s_add_u32 s52, s66, s3
	s_addc_u32 s53, s67, 0
	s_mov_b32 s54, s14
	s_sub_u32 s55, s8, s2
	s_mov_b32 s56, s15
	s_add_u32 s35, s33, 768
	s_cmp_lt_u32 s35, 896
	s_cselect_b32 s35, s35, s39
	s_mov_b64 s[64:65], s[16:17]
	s_mov_b32 s8, 3584
	s_mov_b32 s9, 0x4924925
	s_mov_b32 s12, 56
	s_movk_i32 s13, 0
	s_add_u32 s66, s18, 0x0
	s_addc_u32 s67, s19, 0
	s_movk_i32 s14, 1024
	s_mov_b32 s15, 1
	s_add_u32 s70, s10, 0
	s_addc_u32 s71, s11, 0
.Lcv_z_p3_c:
	s_sub_u32 s0, s35, s13
	s_mul_hi_u32 s1, s0, s9
	s_mul_i32 s2, s1, s12
	s_sub_u32 s2, s0, s2
	s_lshl_b32 s1, s1, 6
	s_lshl_b32 s2, s2, 6
	s_mul_i32 s3, s1, s8
	s_lshl_b32 s3, s3, 2
	s_add_u32 s64, s64, s3
	s_addc_u32 s65, s65, 0
	v_add_u32_e32 v5, s2, v1
	s_sub_u32 s4, s8, 8
	v_min_u32_e32 v5, s4, v5
	v_mad_u32_u24 v5, v0, s8, v5
	v_lshlrev_b32_e32 v5, 2, v5
	global_load_dwordx4 v[70:73], v5, s[64:65]
	global_load_dwordx4 v[74:77], v5, s[64:65] offset:16
	s_lshl_b32 s3, s1, 2
	s_add_u32 s70, s70, s3
	s_addc_u32 s71, s71, 0
	v_lshlrev_b32_e32 v6, 2, v0
	global_load_dword v78, v6, s[70:71]
	s_mul_i32 s3, s2, s14
	s_add_u32 s3, s3, s1
	s_lshl_b32 s3, s3, 1
	s_add_u32 s58, s66, s3
	s_addc_u32 s59, s67, 0
	s_mov_b32 s60, s14
	s_sub_u32 s61, s8, s2
	s_mov_b32 s62, s15
	s_waitcnt vmcnt(0)
.Lcv_z_loop:
	s_add_u32 s35, s33, 0
	s_cmp_ge_u32 s35, 896
	s_cbranch_scc1 .Lcv_z_exit
	s_add_u32 s34, s35, 1024
	s_cmp_lt_u32 s34, 896
	s_cselect_b32 s34, s34, s39
	s_waitcnt vmcnt(13)
	v_cmp_gt_i32_e32 vcc, s43, v1
	s_cmp_eq_u32 s44, 0
	s_cbranch_scc0 .Lcv_z_l0_hs
	v_mov_b32_e32 v48, 1.0
.Lcv_z_l0_hs:
	s_nop 1
	v_mul_f32_e32 v22, v40, v48
	v_cndmask_b32_e32 v22, 0, v22, vcc
	v_mul_f32_e32 v23, v41, v48
	v_cndmask_b32_e32 v23, 0, v23, vcc
	v_mul_f32_e32 v24, v42, v48
	v_cndmask_b32_e32 v24, 0, v24, vcc
	v_mul_f32_e32 v25, v43, v48
	v_cndmask_b32_e32 v25, 0, v25, vcc
	v_mul_f32_e32 v26, v44, v48
	v_cndmask_b32_e32 v26, 0, v26, vcc
	v_mul_f32_e32 v27, v45, v48
	v_cndmask_b32_e32 v27, 0, v27, vcc
	v_mul_f32_e32 v28, v46, v48
	v_cndmask_b32_e32 v28, 0, v28, vcc
	v_mul_f32_e32 v29, v47, v48
	v_cndmask_b32_e32 v29, 0, v29, vcc
	ds_write_b32 v2, v22 offset:0
	ds_write_b32 v2, v23 offset:4
	ds_write_b32 v2, v24 offset:8
	ds_write_b32 v2, v25 offset:12
	ds_write_b32 v2, v26 offset:16
	ds_write_b32 v2, v27 offset:20
	ds_write_b32 v2, v28 offset:24
	ds_write_b32 v2, v29 offset:28
	s_mov_b64 s[36:37], s[40:41]
	s_mov_b32 s38, s42
	s_mov_b64 s[64:65], s[16:17]
	s_mov_b32 s8, 3584
	s_mov_b32 s9, 0x4924925
	s_mov_b32 s12, 56
	s_movk_i32 s13, 0
	s_add_u32 s66, s18, 0x0
	s_addc_u32 s67, s19, 0
	s_movk_i32 s14, 1024
	s_mov_b32 s15, 1
	s_add_u32 s70, s10, 0
	s_addc_u32 s71, s11, 0
.Lcv_z_l0n_c:
	s_sub_u32 s0, s34, s13
	s_mul_hi_u32 s1, s0, s9
	s_mul_i32 s2, s1, s12
	s_sub_u32 s2, s0, s2
	s_lshl_b32 s1, s1, 6
	s_lshl_b32 s2, s2, 6
	s_mul_i32 s3, s1, s8
	s_lshl_b32 s3, s3, 2
	s_add_u32 s64, s64, s3
	s_addc_u32 s65, s65, 0
	v_add_u32_e32 v5, s2, v1
	s_sub_u32 s4, s8, 8
	v_min_u32_e32 v5, s4, v5
	v_mad_u32_u24 v5, v0, s8, v5
	v_lshlrev_b32_e32 v5, 2, v5
	global_load_dwordx4 v[40:43], v5, s[64:65]
	global_load_dwordx4 v[44:47], v5, s[64:65] offset:16
	s_lshl_b32 s3, s1, 2
	s_add_u32 s70, s70, s3
	s_addc_u32 s71, s71, 0
	v_lshlrev_b32_e32 v6, 2, v0
	global_load_dword v48, v6, s[70:71]
	s_mul_i32 s3, s2, s14
	s_add_u32 s3, s3, s1
	s_lshl_b32 s3, s3, 1
	s_add_u32 s40, s66, s3
	s_addc_u32 s41, s67, 0
	s_mov_b32 s42, s14
	s_sub_u32 s43, s8, s2
	s_mov_b32 s44, s15
	s_waitcnt lgkmcnt(0)
	s_barrier
	ds_read_b32 v10, v4 offset:0
	ds_read_b32 v11, v4 offset:260
	ds_read_b32 v12, v4 offset:520
	ds_read_b32 v13, v4 offset:780
	ds_read_b32 v14, v4 offset:1040
	ds_read_b32 v15, v4 offset:1300
	ds_read_b32 v16, v4 offset:1560
	ds_read_b32 v17, v4 offset:1820
	v_mad_u32_u24 v7, v0, s38, v1
	v_lshlrev_b32_e32 v7, 1, v7
	s_waitcnt lgkmcnt(0)
	v_cvt_pk_bf16_f32 v18, v10, v11
	v_cvt_pk_bf16_f32 v19, v12, v13
	v_cvt_pk_bf16_f32 v20, v14, v15
	v_cvt_pk_bf16_f32 v21, v16, v17
	global_store_dwordx4 v7, v[18:21], s[36:37]
	s_add_u32 s35, s33, 256
	s_cmp_ge_u32 s35, 896
	s_cbranch_scc1 .Lcv_z_exit
	s_add_u32 s34, s35, 1024
	s_cmp_lt_u32 s34, 896
	s_cselect_b32 s34, s34, s39
	s_waitcnt vmcnt(13)
	v_cmp_gt_i32_e32 vcc, s49, v1
	s_cmp_eq_u32 s50, 0
	s_cbranch_scc0 .Lcv_z_l1_hs
	v_mov_b32_e32 v58, 1.0
.Lcv_z_l1_hs:
	s_nop 1
	v_mul_f32_e32 v22, v50, v58
	v_cndmask_b32_e32 v22, 0, v22, vcc
	v_mul_f32_e32 v23, v51, v58
	v_cndmask_b32_e32 v23, 0, v23, vcc
	v_mul_f32_e32 v24, v52, v58
	v_cndmask_b32_e32 v24, 0, v24, vcc
	v_mul_f32_e32 v25, v53, v58
	v_cndmask_b32_e32 v25, 0, v25, vcc
	v_mul_f32_e32 v26, v54, v58
	v_cndmask_b32_e32 v26, 0, v26, vcc
	v_mul_f32_e32 v27, v55, v58
	v_cndmask_b32_e32 v27, 0, v27, vcc
	v_mul_f32_e32 v28, v56, v58
	v_cndmask_b32_e32 v28, 0, v28, vcc
	v_mul_f32_e32 v29, v57, v58
	v_cndmask_b32_e32 v29, 0, v29, vcc
	ds_write_b32 v2, v22 offset:16640
	ds_write_b32 v2, v23 offset:16644
	ds_write_b32 v2, v24 offset:16648
	ds_write_b32 v2, v25 offset:16652
	ds_write_b32 v2, v26 offset:16656
	ds_write_b32 v2, v27 offset:16660
	ds_write_b32 v2, v28 offset:16664
	ds_write_b32 v2, v29 offset:16668
	s_mov_b64 s[36:37], s[46:47]
	s_mov_b32 s38, s48
	s_mov_b64 s[64:65], s[16:17]
	s_mov_b32 s8, 3584
	s_mov_b32 s9, 0x4924925
	s_mov_b32 s12, 56
	s_movk_i32 s13, 0
	s_add_u32 s66, s18, 0x0
	s_addc_u32 s67, s19, 0
	s_movk_i32 s14, 1024
	s_mov_b32 s15, 1
	s_add_u32 s70, s10, 0
	s_addc_u32 s71, s11, 0
.Lcv_z_l1n_c:
	s_sub_u32 s0, s34, s13
	s_mul_hi_u32 s1, s0, s9
	s_mul_i32 s2, s1, s12
	s_sub_u32 s2, s0, s2
	s_lshl_b32 s1, s1, 6
	s_lshl_b32 s2, s2, 6
	s_mul_i32 s3, s1, s8
	s_lshl_b32 s3, s3, 2
	s_add_u32 s64, s64, s3
	s_addc_u32 s65, s65, 0
	v_add_u32_e32 v5, s2, v1
	s_sub_u32 s4, s8, 8
	v_min_u32_e32 v5, s4, v5
	v_mad_u32_u24 v5, v0, s8, v5
	v_lshlrev_b32_e32 v5, 2, v5
	global_load_dwordx4 v[50:53], v5, s[64:65]
	global_load_dwordx4 v[54:57], v5, s[64:65] offset:16
	s_lshl_b32 s3, s1, 2
	s_add_u32 s70, s70, s3
	s_addc_u32 s71, s71, 0
	v_lshlrev_b32_e32 v6, 2, v0
	global_load_dword v58, v6, s[70:71]
	s_mul_i32 s3, s2, s14
	s_add_u32 s3, s3, s1
	s_lshl_b32 s3, s3, 1
	s_add_u32 s46, s66, s3
	s_addc_u32 s47, s67, 0
	s_mov_b32 s48, s14
	s_sub_u32 s49, s8, s2
	s_mov_b32 s50, s15
	s_waitcnt lgkmcnt(0)
	s_barrier
	ds_read_b32 v10, v4 offset:16640
	ds_read_b32 v11, v4 offset:16900
	ds_read_b32 v12, v4 offset:17160
	ds_read_b32 v13, v4 offset:17420
	ds_read_b32 v14, v4 offset:17680
	ds_read_b32 v15, v4 offset:17940
	ds_read_b32 v16, v4 offset:18200
	ds_read_b32 v17, v4 offset:18460
	v_mad_u32_u24 v7, v0, s38, v1
	v_lshlrev_b32_e32 v7, 1, v7
	s_waitcnt lgkmcnt(0)
	v_cvt_pk_bf16_f32 v18, v10, v11
	v_cvt_pk_bf16_f32 v19, v12, v13
	v_cvt_pk_bf16_f32 v20, v14, v15
	v_cvt_pk_bf16_f32 v21, v16, v17
	global_store_dwordx4 v7, v[18:21], s[36:37]
	s_add_u32 s35, s33, 512
	s_cmp_ge_u32 s35, 896
	s_cbranch_scc1 .Lcv_z_exit
	s_add_u32 s34, s35, 1024
	s_cmp_lt_u32 s34, 896
	s_cselect_b32 s34, s34, s39
	s_waitcnt vmcnt(13)
	v_cmp_gt_i32_e32 vcc, s55, v1
	s_cmp_eq_u32 s56, 0
	s_cbranch_scc0 .Lcv_z_l2_hs
	v_mov_b32_e32 v68, 1.0
.Lcv_z_l2_hs:
	s_nop 1
	v_mul_f32_e32 v22, v60, v68
	v_cndmask_b32_e32 v22, 0, v22, vcc
	v_mul_f32_e32 v23, v61, v68
	v_cndmask_b32_e32 v23, 0, v23, vcc
	v_mul_f32_e32 v24, v62, v68
	v_cndmask_b32_e32 v24, 0, v24, vcc
	v_mul_f32_e32 v25, v63, v68
	v_cndmask_b32_e32 v25, 0, v25, vcc
	v_mul_f32_e32 v26, v64, v68
	v_cndmask_b32_e32 v26, 0, v26, vcc
	v_mul_f32_e32 v27, v65, v68
	v_cndmask_b32_e32 v27, 0, v27, vcc
	v_mul_f32_e32 v28, v66, v68
	v_cndmask_b32_e32 v28, 0, v28, vcc
	v_mul_f32_e32 v29, v67, v68
	v_cndmask_b32_e32 v29, 0, v29, vcc
	ds_write_b32 v2, v22 offset:0
	ds_write_b32 v2, v23 offset:4
	ds_write_b32 v2, v24 offset:8
	ds_write_b32 v2, v25 offset:12
	ds_write_b32 v2, v26 offset:16
	ds_write_b32 v2, v27 offset:20
	ds_write_b32 v2, v28 offset:24
	ds_write_b32 v2, v29 offset:28
	s_mov_b64 s[36:37], s[52:53]
	s_mov_b32 s38, s54
	s_mov_b64 s[64:65], s[16:17]
	s_mov_b32 s8, 3584
	s_mov_b32 s9, 0x4924925
	s_mov_b32 s12, 56
	s_movk_i32 s13, 0
	s_add_u32 s66, s18, 0x0
	s_addc_u32 s67, s19, 0
	s_movk_i32 s14, 1024
	s_mov_b32 s15, 1
	s_add_u32 s70, s10, 0
	s_addc_u32 s71, s11, 0
.Lcv_z_l2n_c:
	s_sub_u32 s0, s34, s13
	s_mul_hi_u32 s1, s0, s9
	s_mul_i32 s2, s1, s12
	s_sub_u32 s2, s0, s2
	s_lshl_b32 s1, s1, 6
	s_lshl_b32 s2, s2, 6
	s_mul_i32 s3, s1, s8
	s_lshl_b32 s3, s3, 2
	s_add_u32 s64, s64, s3
	s_addc_u32 s65, s65, 0
	v_add_u32_e32 v5, s2, v1
	s_sub_u32 s4, s8, 8
	v_min_u32_e32 v5, s4, v5
	v_mad_u32_u24 v5, v0, s8, v5
	v_lshlrev_b32_e32 v5, 2, v5
	global_load_dwordx4 v[60:63], v5, s[64:65]
	global_load_dwordx4 v[64:67], v5, s[64:65] offset:16
	s_lshl_b32 s3, s1, 2
	s_add_u32 s70, s70, s3
	s_addc_u32 s71, s71, 0
	v_lshlrev_b32_e32 v6, 2, v0
	global_load_dword v68, v6, s[70:71]
	s_mul_i32 s3, s2, s14
	s_add_u32 s3, s3, s1
	s_lshl_b32 s3, s3, 1
	s_add_u32 s52, s66, s3
	s_addc_u32 s53, s67, 0
	s_mov_b32 s54, s14
	s_sub_u32 s55, s8, s2
	s_mov_b32 s56, s15
	s_waitcnt lgkmcnt(0)
	s_barrier
	ds_read_b32 v10, v4 offset:0
	ds_read_b32 v11, v4 offset:260
	ds_read_b32 v12, v4 offset:520
	ds_read_b32 v13, v4 offset:780
	ds_read_b32 v14, v4 offset:1040
	ds_read_b32 v15, v4 offset:1300
	ds_read_b32 v16, v4 offset:1560
	ds_read_b32 v17, v4 offset:1820
	v_mad_u32_u24 v7, v0, s38, v1
	v_lshlrev_b32_e32 v7, 1, v7
	s_waitcnt lgkmcnt(0)
	v_cvt_pk_bf16_f32 v18, v10, v11
	v_cvt_pk_bf16_f32 v19, v12, v13
	v_cvt_pk_bf16_f32 v20, v14, v15
	v_cvt_pk_bf16_f32 v21, v16, v17
	global_store_dwordx4 v7, v[18:21], s[36:37]
	s_add_u32 s35, s33, 768
	s_cmp_ge_u32 s35, 896
	s_cbranch_scc1 .Lcv_z_exit
	s_add_u32 s34, s35, 1024
	s_cmp_lt_u32 s34, 896
	s_cselect_b32 s34, s34, s39
	s_waitcnt vmcnt(13)
	v_cmp_gt_i32_e32 vcc, s61, v1
	s_cmp_eq_u32 s62, 0
	s_cbranch_scc0 .Lcv_z_l3_hs
	v_mov_b32_e32 v78, 1.0
.Lcv_z_l3_hs:
	s_nop 1
	v_mul_f32_e32 v22, v70, v78
	v_cndmask_b32_e32 v22, 0, v22, vcc
	v_mul_f32_e32 v23, v71, v78
	v_cndmask_b32_e32 v23, 0, v23, vcc
	v_mul_f32_e32 v24, v72, v78
	v_cndmask_b32_e32 v24, 0, v24, vcc
	v_mul_f32_e32 v25, v73, v78
	v_cndmask_b32_e32 v25, 0, v25, vcc
	v_mul_f32_e32 v26, v74, v78
	v_cndmask_b32_e32 v26, 0, v26, vcc
	v_mul_f32_e32 v27, v75, v78
	v_cndmask_b32_e32 v27, 0, v27, vcc
	v_mul_f32_e32 v28, v76, v78
	v_cndmask_b32_e32 v28, 0, v28, vcc
	v_mul_f32_e32 v29, v77, v78
	v_cndmask_b32_e32 v29, 0, v29, vcc
	ds_write_b32 v2, v22 offset:16640
	ds_write_b32 v2, v23 offset:16644
	ds_write_b32 v2, v24 offset:16648
	ds_write_b32 v2, v25 offset:16652
	ds_write_b32 v2, v26 offset:16656
	ds_write_b32 v2, v27 offset:16660
	ds_write_b32 v2, v28 offset:16664
	ds_write_b32 v2, v29 offset:16668
	s_mov_b64 s[36:37], s[58:59]
	s_mov_b32 s38, s60
	s_mov_b64 s[64:65], s[16:17]
	s_mov_b32 s8, 3584
	s_mov_b32 s9, 0x4924925
	s_mov_b32 s12, 56
	s_movk_i32 s13, 0
	s_add_u32 s66, s18, 0x0
	s_addc_u32 s67, s19, 0
	s_movk_i32 s14, 1024
	s_mov_b32 s15, 1
	s_add_u32 s70, s10, 0
	s_addc_u32 s71, s11, 0
.Lcv_z_l3n_c:
	s_sub_u32 s0, s34, s13
	s_mul_hi_u32 s1, s0, s9
	s_mul_i32 s2, s1, s12
	s_sub_u32 s2, s0, s2
	s_lshl_b32 s1, s1, 6
	s_lshl_b32 s2, s2, 6
	s_mul_i32 s3, s1, s8
	s_lshl_b32 s3, s3, 2
	s_add_u32 s64, s64, s3
	s_addc_u32 s65, s65, 0
	v_add_u32_e32 v5, s2, v1
	s_sub_u32 s4, s8, 8
	v_min_u32_e32 v5, s4, v5
	v_mad_u32_u24 v5, v0, s8, v5
	v_lshlrev_b32_e32 v5, 2, v5
	global_load_dwordx4 v[70:73], v5, s[64:65]
	global_load_dwordx4 v[74:77], v5, s[64:65] offset:16
	s_lshl_b32 s3, s1, 2
	s_add_u32 s70, s70, s3
	s_addc_u32 s71, s71, 0
	v_lshlrev_b32_e32 v6, 2, v0
	global_load_dword v78, v6, s[70:71]
	s_mul_i32 s3, s2, s14
	s_add_u32 s3, s3, s1
	s_lshl_b32 s3, s3, 1
	s_add_u32 s58, s66, s3
	s_addc_u32 s59, s67, 0
	s_mov_b32 s60, s14
	s_sub_u32 s61, s8, s2
	s_mov_b32 s62, s15
	s_waitcnt lgkmcnt(0)
	s_barrier
	ds_read_b32 v10, v4 offset:16640
	ds_read_b32 v11, v4 offset:16900
	ds_read_b32 v12, v4 offset:17160
	ds_read_b32 v13, v4 offset:17420
	ds_read_b32 v14, v4 offset:17680
	ds_read_b32 v15, v4 offset:17940
	ds_read_b32 v16, v4 offset:18200
	ds_read_b32 v17, v4 offset:18460
	v_mad_u32_u24 v7, v0, s38, v1
	v_lshlrev_b32_e32 v7, 1, v7
	s_waitcnt lgkmcnt(0)
	v_cvt_pk_bf16_f32 v18, v10, v11
	v_cvt_pk_bf16_f32 v19, v12, v13
	v_cvt_pk_bf16_f32 v20, v14, v15
	v_cvt_pk_bf16_f32 v21, v16, v17
	global_store_dwordx4 v7, v[18:21], s[36:37]
	s_add_u32 s33, s33, 1024
	s_branch .Lcv_z_loop
.Lcv_z_exit:
	s_waitcnt vmcnt(0)
	s_barrier
	s_branch .LBB0_64
	s_cmpk_lt_u32 s97, 0x380
	s_cselect_b64 s[4:5], -1, 0
	s_cmpk_gt_u32 s97, 0x37f
	s_cbranch_scc1 .LBB0_63
	s_and_b64 s[2:3], s[4:5], exec
	s_cselect_b32 s1, s97, 0
	s_bfe_u32 s2, s1, 0x100003
	s_mulk_i32 s2, 0x2493
	s_lshr_b32 s2, s2, 16
	s_mul_i32 s3, s2, 0xffffffc8
	s_add_i32 s3, s3, s1
	v_ashrrev_i32_e32 v21, 3, v0
	v_lshlrev_b32_e32 v0, 3, v0
	s_lshl_b32 s12, s3, 6
	v_and_b32_e32 v20, 56, v0
	v_or_b32_e32 v0, s12, v20
	s_movk_i32 s1, 0xe00
	v_cmp_gt_i32_e32 vcc, s1, v0
	v_mov_b32_e32 v0, 0
	v_mov_b32_e32 v2, v0
	v_mov_b32_e32 v3, v0
	s_lshl_b32 s8, s2, 6
	v_mov_b32_e32 v1, v0
	v_mov_b64_e32 v[10:11], v[2:3]
	v_add_u32_e32 v4, s8, v21
	v_lshlrev_b32_e32 v22, 2, v20
	v_mov_b64_e32 v[8:9], v[0:1]
	s_and_saveexec_b64 s[4:5], vcc
	s_cbranch_execz .LBB0_52
	s_movk_i32 s1, 0x3800
	v_mov_b64_e32 v[2:3], s[16:17]
	v_mad_i64_i32 v[2:3], s[2:3], v4, s1, v[2:3]
	s_ashr_i32 s13, s12, 31
	v_lshl_add_u64 v[2:3], s[12:13], 2, v[2:3]
	v_mov_b32_e32 v23, v0
	v_lshl_add_u64 v[6:7], v[2:3], 0, v[22:23]
	global_load_dwordx4 v[0:3], v[6:7], off offset:16
	global_load_dwordx4 v[8:11], v[6:7], off

.LBB0_116:
	s_or_b64 exec, exec, s[4:5]
	s_mov_b64 s[0:1], s[86:87]
	s_waitcnt lgkmcnt(0)
	s_barrier
	s_load_dwordx4 s[24:27], s[0:1], 0x8
	s_load_dwordx8 s[12:19], s[0:1], 0x20
	s_load_dwordx2 s[28:29], s[0:1], 0x88
	s_load_dwordx2 s[10:11], s[0:1], 0xb8
	s_bitcmp1_b32 s97, 0
	s_cselect_b64 s[30:31], -1, 0
	s_and_b64 vcc, exec, s[30:31]
	s_cbranch_vccnz .LBB0_152
	s_waitcnt lgkmcnt(0)
	v_lshrrev_b32_e32 v0, 3, v204
	v_and_b32_e32 v1, 7, v204
	v_lshlrev_b32_e32 v1, 3, v1
	v_mul_u32_u24_e32 v2, 65, v0
	v_add_lshl_u32 v2, v2, v1, 2
	v_mul_u32_u24_e32 v4, 65, v1
	v_add_lshl_u32 v4, v4, v0, 2
	s_add_u32 s39, s97, 896
	s_mov_b32 s33, s39
	s_add_u32 s35, s33, 0
	s_cmp_lt_u32 s35, 4032
	s_cselect_b32 s35, s35, s39
	s_cmp_lt_u32 s35, 1152
	s_cbranch_scc0 .Lcv_a_p0_m1
	s_mov_b64 s[64:65], s[18:19]
	s_mov_b32 s5, 1024
	s_mov_b32 s6, 0x10000000
	s_mov_b32 s7, 16
	s_movk_i32 s8, 896
	s_add_u32 s66, s10, 0x700000
	s_addc_u32 s67, s11, 0
	s_movk_i32 s9, 1024
	s_mov_b32 s20, 0
	s_mov_b64 s[70:71], s[24:25]
	s_branch .Lcv_a_p0_c

.Lcv_a_p0_c:
	s_sub_u32 s0, s35, s8
	s_mul_hi_u32 s1, s0, s6
	s_mul_i32 s2, s1, s7
	s_sub_u32 s2, s0, s2
	s_lshl_b32 s1, s1, 6
	s_lshl_b32 s2, s2, 6
	s_mul_i32 s3, s1, s5
	s_lshl_b32 s3, s3, 2
	s_add_u32 s64, s64, s3
	s_addc_u32 s65, s65, 0
	v_add_u32_e32 v5, s2, v1
	s_sub_u32 s4, s5, 8
	v_min_u32_e32 v5, s4, v5
	v_mad_u32_u24 v5, v0, s5, v5
	v_lshlrev_b32_e32 v5, 2, v5
	global_load_dwordx4 v[40:43], v5, s[64:65]
	global_load_dwordx4 v[44:47], v5, s[64:65] offset:16
	s_lshl_b32 s3, s1, 2
	s_add_u32 s70, s70, s3
	s_addc_u32 s71, s71, 0
	v_lshlrev_b32_e32 v6, 2, v0
	global_load_dword v48, v6, s[70:71]
	s_mul_i32 s3, s2, s9
	s_add_u32 s3, s3, s1
	s_lshl_b32 s3, s3, 1
	s_add_u32 s40, s66, s3
	s_addc_u32 s41, s67, 0
	s_mov_b32 s42, s9
	s_sub_u32 s43, s5, s2
	s_mov_b32 s44, s20
	s_add_u32 s35, s33, 256
	s_cmp_lt_u32 s35, 4032
	s_cselect_b32 s35, s35, s39
	s_cmp_lt_u32 s35, 1152
	s_cbranch_scc0 .Lcv_a_p1_m1
	s_mov_b64 s[64:65], s[18:19]
	s_mov_b32 s5, 1024
	s_mov_b32 s6, 0x10000000
	s_mov_b32 s7, 16
	s_movk_i32 s8, 896
	s_add_u32 s66, s10, 0x700000
	s_addc_u32 s67, s11, 0
	s_movk_i32 s9, 1024
	s_mov_b32 s20, 0
	s_mov_b64 s[70:71], s[24:25]
	s_branch .Lcv_a_p1_c

.Lcv_a_p1_c:
	s_sub_u32 s0, s35, s8
	s_mul_hi_u32 s1, s0, s6
	s_mul_i32 s2, s1, s7
	s_sub_u32 s2, s0, s2
	s_lshl_b32 s1, s1, 6
	s_lshl_b32 s2, s2, 6
	s_mul_i32 s3, s1, s5
	s_lshl_b32 s3, s3, 2
	s_add_u32 s64, s64, s3
	s_addc_u32 s65, s65, 0
	v_add_u32_e32 v5, s2, v1
	s_sub_u32 s4, s5, 8
	v_min_u32_e32 v5, s4, v5
	v_mad_u32_u24 v5, v0, s5, v5
	v_lshlrev_b32_e32 v5, 2, v5
	global_load_dwordx4 v[50:53], v5, s[64:65]
	global_load_dwordx4 v[54:57], v5, s[64:65] offset:16
	s_lshl_b32 s3, s1, 2
	s_add_u32 s70, s70, s3
	s_addc_u32 s71, s71, 0
	v_lshlrev_b32_e32 v6, 2, v0
	global_load_dword v58, v6, s[70:71]
	s_mul_i32 s3, s2, s9
	s_add_u32 s3, s3, s1
	s_lshl_b32 s3, s3, 1
	s_add_u32 s46, s66, s3
	s_addc_u32 s47, s67, 0
	s_mov_b32 s48, s9
	s_sub_u32 s49, s5, s2
	s_mov_b32 s50, s20
	s_add_u32 s35, s33, 512
	s_cmp_lt_u32 s35, 4032
	s_cselect_b32 s35, s35, s39
	s_cmp_lt_u32 s35, 1152
	s_cbranch_scc0 .Lcv_a_p2_m1
	s_mov_b64 s[64:65], s[18:19]
	s_mov_b32 s5, 1024
	s_mov_b32 s6, 0x10000000
	s_mov_b32 s7, 16
	s_movk_i32 s8, 896
	s_add_u32 s66, s10, 0x700000
	s_addc_u32 s67, s11, 0
	s_movk_i32 s9, 1024
	s_mov_b32 s20, 0
	s_mov_b64 s[70:71], s[24:25]
	s_branch .Lcv_a_p2_c

.Lcv_a_p2_c:
	s_sub_u32 s0, s35, s8
	s_mul_hi_u32 s1, s0, s6
	s_mul_i32 s2, s1, s7
	s_sub_u32 s2, s0, s2
	s_lshl_b32 s1, s1, 6
	s_lshl_b32 s2, s2, 6
	s_mul_i32 s3, s1, s5
	s_lshl_b32 s3, s3, 2
	s_add_u32 s64, s64, s3
	s_addc_u32 s65, s65, 0
	v_add_u32_e32 v5, s2, v1
	s_sub_u32 s4, s5, 8
	v_min_u32_e32 v5, s4, v5
	v_mad_u32_u24 v5, v0, s5, v5
	v_lshlrev_b32_e32 v5, 2, v5
	global_load_dwordx4 v[60:63], v5, s[64:65]
	global_load_dwordx4 v[64:67], v5, s[64:65] offset:16
	s_lshl_b32 s3, s1, 2
	s_add_u32 s70, s70, s3
	s_addc_u32 s71, s71, 0
	v_lshlrev_b32_e32 v6, 2, v0
	global_load_dword v68, v6, s[70:71]
	s_mul_i32 s3, s2, s9
	s_add_u32 s3, s3, s1
	s_lshl_b32 s3, s3, 1
	s_add_u32 s52, s66, s3
	s_addc_u32 s53, s67, 0
	s_mov_b32 s54, s9
	s_sub_u32 s55, s5, s2
	s_mov_b32 s56, s20
	s_add_u32 s35, s33, 768
	s_cmp_lt_u32 s35, 4032
	s_cselect_b32 s35, s35, s39
	s_cmp_lt_u32 s35, 1152
	s_cbranch_scc0 .Lcv_a_p3_m1
	s_mov_b64 s[64:65], s[18:19]
	s_mov_b32 s5, 1024
	s_mov_b32 s6, 0x10000000
	s_mov_b32 s7, 16
	s_movk_i32 s8, 896
	s_add_u32 s66, s10, 0x700000
	s_addc_u32 s67, s11, 0
	s_movk_i32 s9, 1024
	s_mov_b32 s20, 0
	s_mov_b64 s[70:71], s[24:25]
	s_branch .Lcv_a_p3_c

.LBB0_164:
	s_andn2_b64 vcc, exec, s[30:31]
	s_cbranch_vccnz .LBB0_200
	s_waitcnt lgkmcnt(0)
	v_lshrrev_b32_e32 v0, 3, v204
	v_and_b32_e32 v1, 7, v204
	v_lshlrev_b32_e32 v1, 3, v1
	v_mul_u32_u24_e32 v2, 65, v0
	v_add_lshl_u32 v2, v2, v1, 2
	v_mul_u32_u24_e32 v4, 65, v1
	v_add_lshl_u32 v4, v4, v0, 2
	s_add_u32 s39, s97, 896
	s_mov_b32 s33, s39
	s_add_u32 s35, s33, 0
	s_cmp_lt_u32 s35, 4032
	s_cselect_b32 s35, s35, s39
	s_cmp_lt_u32 s35, 1152
	s_cbranch_scc0 .Lcv_b_p0_m1
	s_mov_b64 s[64:65], s[18:19]
	s_mov_b32 s5, 1024
	s_mov_b32 s6, 0x10000000
	s_mov_b32 s7, 16
	s_movk_i32 s8, 896
	s_add_u32 s66, s10, 0x700000
	s_addc_u32 s67, s11, 0
	s_movk_i32 s9, 1024
	s_mov_b32 s20, 0
	s_mov_b64 s[70:71], s[24:25]
	s_branch .Lcv_b_p0_c
